# convert_weights gather loops: one trip with 32 global loads in flight per item (was two trips of 16)
# baseline (speedup 1.0000x reference)
; #define LAS __attribute__((address_space(3)))
; __device__ __forceinline__ void transpose_item(const float* W, int K, int N, bf16_t* WT, LAS float* scr, int item, int lane) {
;     const int nblk = N / 32, kb = item / nblk, nb = item % nblk, k0 = 64 * kb, n0 = 32 * nb;
; #pragma unroll 8
;     for (int i = 0; i < 32; ++i) { const int kk = 2 * i + (lane >> 5); scr[kk * 33 + (lane & 31)] = W[(size_t)(k0 + kk) * N + n0 + (lane & 31)]; }
;     asm volatile("s_waitcnt lgkmcnt(0)" ::: "memory");
.Lcw_gather1:
	s_lshl_b32 s13, s10, 1
	s_lshl_b32 s12, s2, 1
	v_or_b32_e32 v80, s13, v18
	v_or_b32_e32 v81, s12, v5
	v_or_b32_e32 v82, s13, v2
	v_or_b32_e32 v83, s12, v3
	v_add_u32_e32 v88, 0, v80
	v_mov_b32_e32 v89, v1
	v_lshlrev_b64 v[84:85], 12, v[88:89]
	v_lshl_add_u64 v[84:85], v[16:17], 0, v[84:85]
	global_load_dword v48, v[84:85], off
	v_add_u32_e32 v88, 0, v81
	v_mov_b32_e32 v89, v1
	v_lshlrev_b64 v[86:87], 12, v[88:89]
	v_lshl_add_u64 v[86:87], v[16:17], 0, v[86:87]
	global_load_dword v49, v[86:87], off
	v_add_u32_e32 v88, 4, v80
	v_mov_b32_e32 v89, v1
	v_lshlrev_b64 v[84:85], 12, v[88:89]
	v_lshl_add_u64 v[84:85], v[16:17], 0, v[84:85]
	global_load_dword v50, v[84:85], off
	v_add_u32_e32 v88, 4, v81
	v_mov_b32_e32 v89, v1
	v_lshlrev_b64 v[86:87], 12, v[88:89]
	v_lshl_add_u64 v[86:87], v[16:17], 0, v[86:87]
	global_load_dword v51, v[86:87], off
	v_add_u32_e32 v88, 8, v80
	v_mov_b32_e32 v89, v1
	v_lshlrev_b64 v[84:85], 12, v[88:89]
	v_lshl_add_u64 v[84:85], v[16:17], 0, v[84:85]
	global_load_dword v52, v[84:85], off
	v_add_u32_e32 v88, 8, v81
	v_mov_b32_e32 v89, v1
	v_lshlrev_b64 v[86:87], 12, v[88:89]
	v_lshl_add_u64 v[86:87], v[16:17], 0, v[86:87]
	global_load_dword v53, v[86:87], off
	v_add_u32_e32 v88, 12, v80
	v_mov_b32_e32 v89, v1
	v_lshlrev_b64 v[84:85], 12, v[88:89]
	v_lshl_add_u64 v[84:85], v[16:17], 0, v[84:85]
	global_load_dword v54, v[84:85], off
	v_add_u32_e32 v88, 12, v81
	v_mov_b32_e32 v89, v1
	v_lshlrev_b64 v[86:87], 12, v[88:89]
	v_lshl_add_u64 v[86:87], v[16:17], 0, v[86:87]
	global_load_dword v55, v[86:87], off
	v_add_u32_e32 v88, 16, v80
	v_mov_b32_e32 v89, v1
	v_lshlrev_b64 v[84:85], 12, v[88:89]
	v_lshl_add_u64 v[84:85], v[16:17], 0, v[84:85]
	global_load_dword v56, v[84:85], off
	v_add_u32_e32 v88, 16, v81
	v_mov_b32_e32 v89, v1
	v_lshlrev_b64 v[86:87], 12, v[88:89]
	v_lshl_add_u64 v[86:87], v[16:17], 0, v[86:87]
	global_load_dword v57, v[86:87], off
	v_add_u32_e32 v88, 20, v80
	v_mov_b32_e32 v89, v1
	v_lshlrev_b64 v[84:85], 12, v[88:89]
	v_lshl_add_u64 v[84:85], v[16:17], 0, v[84:85]
	global_load_dword v58, v[84:85], off
	v_add_u32_e32 v88, 20, v81
	v_mov_b32_e32 v89, v1
	v_lshlrev_b64 v[86:87], 12, v[88:89]
	v_lshl_add_u64 v[86:87], v[16:17], 0, v[86:87]
	global_load_dword v59, v[86:87], off
	v_add_u32_e32 v88, 24, v80
	v_mov_b32_e32 v89, v1
	v_lshlrev_b64 v[84:85], 12, v[88:89]
	v_lshl_add_u64 v[84:85], v[16:17], 0, v[84:85]
	global_load_dword v60, v[84:85], off
	v_add_u32_e32 v88, 24, v81
	v_mov_b32_e32 v89, v1
	v_lshlrev_b64 v[86:87], 12, v[88:89]
	v_lshl_add_u64 v[86:87], v[16:17], 0, v[86:87]
	global_load_dword v61, v[86:87], off
	v_add_u32_e32 v88, 28, v80
	v_mov_b32_e32 v89, v1
	v_lshlrev_b64 v[84:85], 12, v[88:89]
	v_lshl_add_u64 v[84:85], v[16:17], 0, v[84:85]
	global_load_dword v62, v[84:85], off
	v_add_u32_e32 v88, 28, v81
	v_mov_b32_e32 v89, v1
	v_lshlrev_b64 v[86:87], 12, v[88:89]
	v_lshl_add_u64 v[86:87], v[16:17], 0, v[86:87]
	global_load_dword v63, v[86:87], off
	v_add_u32_e32 v88, 32, v80
	v_mov_b32_e32 v89, v1
	v_lshlrev_b64 v[84:85], 12, v[88:89]
	v_lshl_add_u64 v[84:85], v[16:17], 0, v[84:85]
	global_load_dword v64, v[84:85], off
	v_add_u32_e32 v88, 32, v81
	v_mov_b32_e32 v89, v1
	v_lshlrev_b64 v[86:87], 12, v[88:89]
	v_lshl_add_u64 v[86:87], v[16:17], 0, v[86:87]
	global_load_dword v65, v[86:87], off
	v_add_u32_e32 v88, 36, v80
	v_mov_b32_e32 v89, v1
	v_lshlrev_b64 v[84:85], 12, v[88:89]
	v_lshl_add_u64 v[84:85], v[16:17], 0, v[84:85]
	global_load_dword v66, v[84:85], off
	v_add_u32_e32 v88, 36, v81
	v_mov_b32_e32 v89, v1
	v_lshlrev_b64 v[86:87], 12, v[88:89]
	v_lshl_add_u64 v[86:87], v[16:17], 0, v[86:87]
	global_load_dword v67, v[86:87], off
	v_add_u32_e32 v88, 40, v80
	v_mov_b32_e32 v89, v1
	v_lshlrev_b64 v[84:85], 12, v[88:89]
	v_lshl_add_u64 v[84:85], v[16:17], 0, v[84:85]
	global_load_dword v68, v[84:85], off
	v_add_u32_e32 v88, 40, v81
	v_mov_b32_e32 v89, v1
	v_lshlrev_b64 v[86:87], 12, v[88:89]
	v_lshl_add_u64 v[86:87], v[16:17], 0, v[86:87]
	global_load_dword v69, v[86:87], off
	v_add_u32_e32 v88, 44, v80
	v_mov_b32_e32 v89, v1
	v_lshlrev_b64 v[84:85], 12, v[88:89]
	v_lshl_add_u64 v[84:85], v[16:17], 0, v[84:85]
	global_load_dword v70, v[84:85], off
	v_add_u32_e32 v88, 44, v81
	v_mov_b32_e32 v89, v1
	v_lshlrev_b64 v[86:87], 12, v[88:89]
	v_lshl_add_u64 v[86:87], v[16:17], 0, v[86:87]
	global_load_dword v71, v[86:87], off
	v_add_u32_e32 v88, 48, v80
	v_mov_b32_e32 v89, v1
	v_lshlrev_b64 v[84:85], 12, v[88:89]
	v_lshl_add_u64 v[84:85], v[16:17], 0, v[84:85]
	global_load_dword v72, v[84:85], off
	v_add_u32_e32 v88, 48, v81
	v_mov_b32_e32 v89, v1
	v_lshlrev_b64 v[86:87], 12, v[88:89]
	v_lshl_add_u64 v[86:87], v[16:17], 0, v[86:87]
	global_load_dword v73, v[86:87], off
	v_add_u32_e32 v88, 52, v80
	v_mov_b32_e32 v89, v1
	v_lshlrev_b64 v[84:85], 12, v[88:89]
	v_lshl_add_u64 v[84:85], v[16:17], 0, v[84:85]
	global_load_dword v74, v[84:85], off
	v_add_u32_e32 v88, 52, v81
	v_mov_b32_e32 v89, v1
	v_lshlrev_b64 v[86:87], 12, v[88:89]
	v_lshl_add_u64 v[86:87], v[16:17], 0, v[86:87]
	global_load_dword v75, v[86:87], off
	v_add_u32_e32 v88, 56, v80
	v_mov_b32_e32 v89, v1
	v_lshlrev_b64 v[84:85], 12, v[88:89]
	v_lshl_add_u64 v[84:85], v[16:17], 0, v[84:85]
	global_load_dword v76, v[84:85], off
	v_add_u32_e32 v88, 56, v81
	v_mov_b32_e32 v89, v1
	v_lshlrev_b64 v[86:87], 12, v[88:89]
	v_lshl_add_u64 v[86:87], v[16:17], 0, v[86:87]
	global_load_dword v77, v[86:87], off
	v_add_u32_e32 v88, 60, v80
	v_mov_b32_e32 v89, v1
	v_lshlrev_b64 v[84:85], 12, v[88:89]
	v_lshl_add_u64 v[84:85], v[16:17], 0, v[84:85]
	global_load_dword v78, v[84:85], off
	v_add_u32_e32 v88, 60, v81
	v_mov_b32_e32 v89, v1
	v_lshlrev_b64 v[86:87], 12, v[88:89]
	v_lshl_add_u64 v[86:87], v[16:17], 0, v[86:87]
	global_load_dword v79, v[86:87], off
	v_add_u32_e32 v88, 0, v82
	v_mad_u64_u32 v[84:85], s[14:15], v88, s91, v[4:5]
	s_waitcnt vmcnt(31)
; #define LAS __attribute__((address_space(3)))
; __device__ __forceinline__ unsigned pk2(float lo, float hi) { f32x2 v = {lo, hi}; hbf16x2 b = __builtin_convertvector(v, hbf16x2); return __builtin_bit_cast(unsigned, b); }
; __device__ __forceinline__ void transpose_item(const float* W, int K, int N, bf16_t* WT, LAS float* scr, int item, int lane) {
;     ...
;     for (int i = 0; i < 32; ++i) { const int kk = 2 * i + (lane >> 5); scr[kk * 33 + (lane & 31)] = W[(size_t)(k0 + kk) * N + n0 + (lane & 31)]; }
;     asm volatile("s_waitcnt lgkmcnt(0)" ::: "memory");
;     const int c = lane & 7;
; #pragma unroll
;     for (int j = 0; j < 4; ++j) { const int n = (lane >> 3) + 8 * j; const LAS float* s = scr + (8 * c) * 33 + n;
;         u32x4 o; o.x = pk2(s[0 * 33], s[1 * 33]); o.y = pk2(s[2 * 33], s[3 * 33]); o.z = pk2(s[4 * 33], s[5 * 33]); o.w = pk2(s[6 * 33], s[7 * 33]);
;         *(u32x4*)(WT + (size_t)(n0 + n) * K + k0 + 8 * c) = o; }
;     asm volatile("s_waitcnt lgkmcnt(0)" ::: "memory");
; }
	ds_write_b32 v84, v48
	v_add_u32_e32 v88, 0, v83
	v_mad_u64_u32 v[86:87], s[14:15], v88, s91, v[4:5]
	s_waitcnt vmcnt(30)
	ds_write_b32 v86, v49
	v_add_u32_e32 v88, 4, v82
	v_mad_u64_u32 v[84:85], s[14:15], v88, s91, v[4:5]
	s_waitcnt vmcnt(29)
	ds_write_b32 v84, v50
	v_add_u32_e32 v88, 4, v83
	v_mad_u64_u32 v[86:87], s[14:15], v88, s91, v[4:5]
	s_waitcnt vmcnt(28)
	ds_write_b32 v86, v51
	v_add_u32_e32 v88, 8, v82
	v_mad_u64_u32 v[84:85], s[14:15], v88, s91, v[4:5]
	s_waitcnt vmcnt(27)
	ds_write_b32 v84, v52
	v_add_u32_e32 v88, 8, v83
	v_mad_u64_u32 v[86:87], s[14:15], v88, s91, v[4:5]
	s_waitcnt vmcnt(26)
	ds_write_b32 v86, v53
	v_add_u32_e32 v88, 12, v82
	v_mad_u64_u32 v[84:85], s[14:15], v88, s91, v[4:5]
	s_waitcnt vmcnt(25)
	ds_write_b32 v84, v54
	v_add_u32_e32 v88, 12, v83
	v_mad_u64_u32 v[86:87], s[14:15], v88, s91, v[4:5]
	s_waitcnt vmcnt(24)
	ds_write_b32 v86, v55
	v_add_u32_e32 v88, 16, v82
	v_mad_u64_u32 v[84:85], s[14:15], v88, s91, v[4:5]
	s_waitcnt vmcnt(23)
	ds_write_b32 v84, v56
	v_add_u32_e32 v88, 16, v83
	v_mad_u64_u32 v[86:87], s[14:15], v88, s91, v[4:5]
	s_waitcnt vmcnt(22)
	ds_write_b32 v86, v57
	v_add_u32_e32 v88, 20, v82
	v_mad_u64_u32 v[84:85], s[14:15], v88, s91, v[4:5]
	s_waitcnt vmcnt(21)
	ds_write_b32 v84, v58
	v_add_u32_e32 v88, 20, v83
	v_mad_u64_u32 v[86:87], s[14:15], v88, s91, v[4:5]
	s_waitcnt vmcnt(20)
	ds_write_b32 v86, v59
	v_add_u32_e32 v88, 24, v82
	v_mad_u64_u32 v[84:85], s[14:15], v88, s91, v[4:5]
	s_waitcnt vmcnt(19)
	ds_write_b32 v84, v60
	v_add_u32_e32 v88, 24, v83
	v_mad_u64_u32 v[86:87], s[14:15], v88, s91, v[4:5]
	s_waitcnt vmcnt(18)
	ds_write_b32 v86, v61
	v_add_u32_e32 v88, 28, v82
	v_mad_u64_u32 v[84:85], s[14:15], v88, s91, v[4:5]
	s_waitcnt vmcnt(17)
	ds_write_b32 v84, v62
	v_add_u32_e32 v88, 28, v83
	v_mad_u64_u32 v[86:87], s[14:15], v88, s91, v[4:5]
	s_waitcnt vmcnt(16)
	ds_write_b32 v86, v63
	v_add_u32_e32 v88, 32, v82
	v_mad_u64_u32 v[84:85], s[14:15], v88, s91, v[4:5]
	s_waitcnt vmcnt(15)
	ds_write_b32 v84, v64
	v_add_u32_e32 v88, 32, v83
	v_mad_u64_u32 v[86:87], s[14:15], v88, s91, v[4:5]
	s_waitcnt vmcnt(14)
	ds_write_b32 v86, v65
	v_add_u32_e32 v88, 36, v82
	v_mad_u64_u32 v[84:85], s[14:15], v88, s91, v[4:5]
	s_waitcnt vmcnt(13)
	ds_write_b32 v84, v66
	v_add_u32_e32 v88, 36, v83
	v_mad_u64_u32 v[86:87], s[14:15], v88, s91, v[4:5]
	s_waitcnt vmcnt(12)
	ds_write_b32 v86, v67
	v_add_u32_e32 v88, 40, v82
	v_mad_u64_u32 v[84:85], s[14:15], v88, s91, v[4:5]
	s_waitcnt vmcnt(11)
	ds_write_b32 v84, v68
	v_add_u32_e32 v88, 40, v83
	v_mad_u64_u32 v[86:87], s[14:15], v88, s91, v[4:5]
	s_waitcnt vmcnt(10)
	ds_write_b32 v86, v69
	v_add_u32_e32 v88, 44, v82
	v_mad_u64_u32 v[84:85], s[14:15], v88, s91, v[4:5]
	s_waitcnt vmcnt(9)
	ds_write_b32 v84, v70
	v_add_u32_e32 v88, 44, v83
	v_mad_u64_u32 v[86:87], s[14:15], v88, s91, v[4:5]
	s_waitcnt vmcnt(8)
	ds_write_b32 v86, v71
	v_add_u32_e32 v88, 48, v82
	v_mad_u64_u32 v[84:85], s[14:15], v88, s91, v[4:5]
	s_waitcnt vmcnt(7)
	ds_write_b32 v84, v72
	v_add_u32_e32 v88, 48, v83
	v_mad_u64_u32 v[86:87], s[14:15], v88, s91, v[4:5]
	s_waitcnt vmcnt(6)
	ds_write_b32 v86, v73
	v_add_u32_e32 v88, 52, v82
	v_mad_u64_u32 v[84:85], s[14:15], v88, s91, v[4:5]
	s_waitcnt vmcnt(5)
	ds_write_b32 v84, v74
	v_add_u32_e32 v88, 52, v83
	v_mad_u64_u32 v[86:87], s[14:15], v88, s91, v[4:5]
	s_waitcnt vmcnt(4)
	ds_write_b32 v86, v75
	v_add_u32_e32 v88, 56, v82
	v_mad_u64_u32 v[84:85], s[14:15], v88, s91, v[4:5]
	s_waitcnt vmcnt(3)
	ds_write_b32 v84, v76
	v_add_u32_e32 v88, 56, v83
	v_mad_u64_u32 v[86:87], s[14:15], v88, s91, v[4:5]
	s_waitcnt vmcnt(2)
	ds_write_b32 v86, v77
	v_add_u32_e32 v88, 60, v82
	v_mad_u64_u32 v[84:85], s[14:15], v88, s91, v[4:5]
	s_waitcnt vmcnt(1)
	ds_write_b32 v84, v78
	v_add_u32_e32 v88, 60, v83
	v_mad_u64_u32 v[86:87], s[14:15], v88, s91, v[4:5]
	s_waitcnt vmcnt(0)
	ds_write_b32 v86, v79
	s_add_i32 s10, s10, 32
	s_add_i32 s2, s2, 32
	s_add_i32 s11, s11, -32
	s_cmp_lg_u32 s11, 0
	s_cbranch_scc1 .Lcw_gather1
	s_waitcnt lgkmcnt(0)
	ds_read2_b32 v[30:31], v23 offset0:33 offset1:41
	ds_read2_b32 v[32:33], v23 offset1:8
	ds_read2_b32 v[34:35], v23 offset0:66 offset1:74
	ds_read2_b32 v[36:37], v23 offset0:99 offset1:107
	ds_read2_b32 v[38:39], v23 offset0:132 offset1:140
	ds_read2_b32 v[40:41], v23 offset0:165 offset1:173
	ds_read2_b32 v[42:43], v23 offset0:198 offset1:206
	ds_read2_b32 v[44:45], v23 offset0:231 offset1:239
	v_lshlrev_b32_e32 v0, 1, v15
	v_lshl_add_u64 v[28:29], v[8:9], 0, v[0:1]
	v_or_b32_e32 v0, v21, v22
	v_lshlrev_b32_e32 v0, 11, v0
	v_lshl_add_u64 v[46:47], v[28:29], 0, v[0:1]
	v_or_b32_e32 v0, v21, v24
	s_waitcnt lgkmcnt(6)
	v_cvt_pk_bf16_f32 v16, v32, v30
	s_waitcnt lgkmcnt(4)
	v_cvt_pk_bf16_f32 v17, v34, v36
	s_waitcnt lgkmcnt(2)
	v_cvt_pk_bf16_f32 v18, v38, v40
	s_waitcnt lgkmcnt(0)
	v_cvt_pk_bf16_f32 v19, v42, v44
	v_lshlrev_b32_e32 v0, 11, v0
	global_store_dwordx4 v[46:47], v[16:19], off
	s_nop 1
	v_cvt_pk_bf16_f32 v16, v33, v31
	v_cvt_pk_bf16_f32 v17, v35, v37
	v_cvt_pk_bf16_f32 v18, v39, v41
	v_cvt_pk_bf16_f32 v19, v43, v45
	v_lshl_add_u64 v[30:31], v[28:29], 0, v[0:1]
	global_store_dwordx4 v[30:31], v[16:19], off
	ds_read2_b32 v[30:31], v23 offset0:49 offset1:57
	ds_read2_b32 v[32:33], v23 offset0:16 offset1:24
	ds_read2_b32 v[34:35], v23 offset0:82 offset1:90
	ds_read2_b32 v[36:37], v23 offset0:115 offset1:123
	ds_read2_b32 v[38:39], v23 offset0:148 offset1:156
	ds_read2_b32 v[40:41], v23 offset0:181 offset1:189
	ds_read2_b32 v[42:43], v23 offset0:214 offset1:222
	ds_read2_b32 v[44:45], v23 offset0:247 offset1:255
	v_or_b32_e32 v0, v21, v25
	v_lshlrev_b32_e32 v0, 11, v0
	v_lshl_add_u64 v[46:47], v[28:29], 0, v[0:1]
	v_or_b32_e32 v0, v21, v26
	s_waitcnt lgkmcnt(6)
	v_cvt_pk_bf16_f32 v16, v32, v30
	s_waitcnt lgkmcnt(4)
	v_cvt_pk_bf16_f32 v17, v34, v36
	s_waitcnt lgkmcnt(2)
	v_cvt_pk_bf16_f32 v18, v38, v40
	s_waitcnt lgkmcnt(0)
	v_cvt_pk_bf16_f32 v19, v42, v44
	v_lshlrev_b32_e32 v0, 11, v0
	global_store_dwordx4 v[46:47], v[16:19], off
	v_lshl_add_u64 v[20:21], v[28:29], 0, v[0:1]
	s_nop 0
	v_cvt_pk_bf16_f32 v16, v33, v31
	v_cvt_pk_bf16_f32 v17, v35, v37
	v_cvt_pk_bf16_f32 v18, v39, v41
	v_cvt_pk_bf16_f32 v19, v43, v45
	global_store_dwordx4 v[20:21], v[16:19], off
	s_waitcnt lgkmcnt(0)

; #define LAS __attribute__((address_space(3)))
; __device__ __forceinline__ void transpose_item(const float* W, int K, int N, bf16_t* WT, LAS float* scr, int item, int lane) {
;     const int nblk = N / 32, kb = item / nblk, nb = item % nblk, k0 = 64 * kb, n0 = 32 * nb;
; #pragma unroll 8
;     for (int i = 0; i < 32; ++i) { const int kk = 2 * i + (lane >> 5); scr[kk * 33 + (lane & 31)] = W[(size_t)(k0 + kk) * N + n0 + (lane & 31)]; }
;     asm volatile("s_waitcnt lgkmcnt(0)" ::: "memory");
.Lcw_gather2:
	s_lshl_b32 s13, s10, 1
	s_lshl_b32 s12, s2, 1
	v_or_b32_e32 v80, s13, v20
	v_or_b32_e32 v81, s12, v5
	v_or_b32_e32 v82, s13, v2
	v_or_b32_e32 v83, s12, v3
	v_add_u32_e32 v88, 0, v80
	v_mov_b32_e32 v89, v1
	v_lshlrev_b64 v[84:85], 12, v[88:89]
	v_lshl_add_u64 v[84:85], v[18:19], 0, v[84:85]
	global_load_dword v48, v[84:85], off
	v_add_u32_e32 v88, 0, v81
	v_mov_b32_e32 v89, v1
	v_lshlrev_b64 v[86:87], 12, v[88:89]
	v_lshl_add_u64 v[86:87], v[18:19], 0, v[86:87]
	global_load_dword v49, v[86:87], off
	v_add_u32_e32 v88, 4, v80
	v_mov_b32_e32 v89, v1
	v_lshlrev_b64 v[84:85], 12, v[88:89]
	v_lshl_add_u64 v[84:85], v[18:19], 0, v[84:85]
	global_load_dword v50, v[84:85], off
	v_add_u32_e32 v88, 4, v81
	v_mov_b32_e32 v89, v1
	v_lshlrev_b64 v[86:87], 12, v[88:89]
	v_lshl_add_u64 v[86:87], v[18:19], 0, v[86:87]
	global_load_dword v51, v[86:87], off
	v_add_u32_e32 v88, 8, v80
	v_mov_b32_e32 v89, v1
	v_lshlrev_b64 v[84:85], 12, v[88:89]
	v_lshl_add_u64 v[84:85], v[18:19], 0, v[84:85]
	global_load_dword v52, v[84:85], off
	v_add_u32_e32 v88, 8, v81
	v_mov_b32_e32 v89, v1
	v_lshlrev_b64 v[86:87], 12, v[88:89]
	v_lshl_add_u64 v[86:87], v[18:19], 0, v[86:87]
	global_load_dword v53, v[86:87], off
	v_add_u32_e32 v88, 12, v80
	v_mov_b32_e32 v89, v1
	v_lshlrev_b64 v[84:85], 12, v[88:89]
	v_lshl_add_u64 v[84:85], v[18:19], 0, v[84:85]
	global_load_dword v54, v[84:85], off
	v_add_u32_e32 v88, 12, v81
	v_mov_b32_e32 v89, v1
	v_lshlrev_b64 v[86:87], 12, v[88:89]
	v_lshl_add_u64 v[86:87], v[18:19], 0, v[86:87]
	global_load_dword v55, v[86:87], off
	v_add_u32_e32 v88, 16, v80
	v_mov_b32_e32 v89, v1
	v_lshlrev_b64 v[84:85], 12, v[88:89]
	v_lshl_add_u64 v[84:85], v[18:19], 0, v[84:85]
	global_load_dword v56, v[84:85], off
	v_add_u32_e32 v88, 16, v81
	v_mov_b32_e32 v89, v1
	v_lshlrev_b64 v[86:87], 12, v[88:89]
	v_lshl_add_u64 v[86:87], v[18:19], 0, v[86:87]
	global_load_dword v57, v[86:87], off
	v_add_u32_e32 v88, 20, v80
	v_mov_b32_e32 v89, v1
	v_lshlrev_b64 v[84:85], 12, v[88:89]
	v_lshl_add_u64 v[84:85], v[18:19], 0, v[84:85]
	global_load_dword v58, v[84:85], off
	v_add_u32_e32 v88, 20, v81
	v_mov_b32_e32 v89, v1
	v_lshlrev_b64 v[86:87], 12, v[88:89]
	v_lshl_add_u64 v[86:87], v[18:19], 0, v[86:87]
	global_load_dword v59, v[86:87], off
	v_add_u32_e32 v88, 24, v80
	v_mov_b32_e32 v89, v1
	v_lshlrev_b64 v[84:85], 12, v[88:89]
	v_lshl_add_u64 v[84:85], v[18:19], 0, v[84:85]
	global_load_dword v60, v[84:85], off
	v_add_u32_e32 v88, 24, v81
	v_mov_b32_e32 v89, v1
	v_lshlrev_b64 v[86:87], 12, v[88:89]
	v_lshl_add_u64 v[86:87], v[18:19], 0, v[86:87]
	global_load_dword v61, v[86:87], off
	v_add_u32_e32 v88, 28, v80
	v_mov_b32_e32 v89, v1
	v_lshlrev_b64 v[84:85], 12, v[88:89]
	v_lshl_add_u64 v[84:85], v[18:19], 0, v[84:85]
	global_load_dword v62, v[84:85], off
	v_add_u32_e32 v88, 28, v81
	v_mov_b32_e32 v89, v1
	v_lshlrev_b64 v[86:87], 12, v[88:89]
	v_lshl_add_u64 v[86:87], v[18:19], 0, v[86:87]
	global_load_dword v63, v[86:87], off
	v_add_u32_e32 v88, 32, v80
	v_mov_b32_e32 v89, v1
	v_lshlrev_b64 v[84:85], 12, v[88:89]
	v_lshl_add_u64 v[84:85], v[18:19], 0, v[84:85]
	global_load_dword v64, v[84:85], off
	v_add_u32_e32 v88, 32, v81
	v_mov_b32_e32 v89, v1
	v_lshlrev_b64 v[86:87], 12, v[88:89]
	v_lshl_add_u64 v[86:87], v[18:19], 0, v[86:87]
	global_load_dword v65, v[86:87], off
	v_add_u32_e32 v88, 36, v80
	v_mov_b32_e32 v89, v1
	v_lshlrev_b64 v[84:85], 12, v[88:89]
	v_lshl_add_u64 v[84:85], v[18:19], 0, v[84:85]
	global_load_dword v66, v[84:85], off
	v_add_u32_e32 v88, 36, v81
	v_mov_b32_e32 v89, v1
	v_lshlrev_b64 v[86:87], 12, v[88:89]
	v_lshl_add_u64 v[86:87], v[18:19], 0, v[86:87]
	global_load_dword v67, v[86:87], off
	v_add_u32_e32 v88, 40, v80
	v_mov_b32_e32 v89, v1
	v_lshlrev_b64 v[84:85], 12, v[88:89]
	v_lshl_add_u64 v[84:85], v[18:19], 0, v[84:85]
	global_load_dword v68, v[84:85], off
	v_add_u32_e32 v88, 40, v81
	v_mov_b32_e32 v89, v1
	v_lshlrev_b64 v[86:87], 12, v[88:89]
	v_lshl_add_u64 v[86:87], v[18:19], 0, v[86:87]
	global_load_dword v69, v[86:87], off
	v_add_u32_e32 v88, 44, v80
	v_mov_b32_e32 v89, v1
	v_lshlrev_b64 v[84:85], 12, v[88:89]
	v_lshl_add_u64 v[84:85], v[18:19], 0, v[84:85]
	global_load_dword v70, v[84:85], off
	v_add_u32_e32 v88, 44, v81
	v_mov_b32_e32 v89, v1
	v_lshlrev_b64 v[86:87], 12, v[88:89]
	v_lshl_add_u64 v[86:87], v[18:19], 0, v[86:87]
	global_load_dword v71, v[86:87], off
	v_add_u32_e32 v88, 48, v80
	v_mov_b32_e32 v89, v1
	v_lshlrev_b64 v[84:85], 12, v[88:89]
	v_lshl_add_u64 v[84:85], v[18:19], 0, v[84:85]
	global_load_dword v72, v[84:85], off
	v_add_u32_e32 v88, 48, v81
	v_mov_b32_e32 v89, v1
	v_lshlrev_b64 v[86:87], 12, v[88:89]
	v_lshl_add_u64 v[86:87], v[18:19], 0, v[86:87]
	global_load_dword v73, v[86:87], off
	v_add_u32_e32 v88, 52, v80
	v_mov_b32_e32 v89, v1
	v_lshlrev_b64 v[84:85], 12, v[88:89]
	v_lshl_add_u64 v[84:85], v[18:19], 0, v[84:85]
	global_load_dword v74, v[84:85], off
	v_add_u32_e32 v88, 52, v81
	v_mov_b32_e32 v89, v1
	v_lshlrev_b64 v[86:87], 12, v[88:89]
	v_lshl_add_u64 v[86:87], v[18:19], 0, v[86:87]
	global_load_dword v75, v[86:87], off
	v_add_u32_e32 v88, 56, v80
	v_mov_b32_e32 v89, v1
	v_lshlrev_b64 v[84:85], 12, v[88:89]
	v_lshl_add_u64 v[84:85], v[18:19], 0, v[84:85]
	global_load_dword v76, v[84:85], off
	v_add_u32_e32 v88, 56, v81
	v_mov_b32_e32 v89, v1
	v_lshlrev_b64 v[86:87], 12, v[88:89]
	v_lshl_add_u64 v[86:87], v[18:19], 0, v[86:87]
	global_load_dword v77, v[86:87], off
	v_add_u32_e32 v88, 60, v80
	v_mov_b32_e32 v89, v1
	v_lshlrev_b64 v[84:85], 12, v[88:89]
	v_lshl_add_u64 v[84:85], v[18:19], 0, v[84:85]
	global_load_dword v78, v[84:85], off
	v_add_u32_e32 v88, 60, v81
	v_mov_b32_e32 v89, v1
	v_lshlrev_b64 v[86:87], 12, v[88:89]
	v_lshl_add_u64 v[86:87], v[18:19], 0, v[86:87]
	global_load_dword v79, v[86:87], off
	v_add_u32_e32 v88, 0, v82
	v_mad_u64_u32 v[84:85], s[14:15], v88, s91, v[4:5]
	s_waitcnt vmcnt(31)
; #define LAS __attribute__((address_space(3)))
; __device__ __forceinline__ unsigned pk2(float lo, float hi) { f32x2 v = {lo, hi}; hbf16x2 b = __builtin_convertvector(v, hbf16x2); return __builtin_bit_cast(unsigned, b); }
; __device__ __forceinline__ void transpose_item(const float* W, int K, int N, bf16_t* WT, LAS float* scr, int item, int lane) {
;     ...
;     for (int i = 0; i < 32; ++i) { const int kk = 2 * i + (lane >> 5); scr[kk * 33 + (lane & 31)] = W[(size_t)(k0 + kk) * N + n0 + (lane & 31)]; }
;     asm volatile("s_waitcnt lgkmcnt(0)" ::: "memory");
;     const int c = lane & 7;
; #pragma unroll
;     for (int j = 0; j < 4; ++j) { const int n = (lane >> 3) + 8 * j; const LAS float* s = scr + (8 * c) * 33 + n;
;         u32x4 o; o.x = pk2(s[0 * 33], s[1 * 33]); o.y = pk2(s[2 * 33], s[3 * 33]); o.z = pk2(s[4 * 33], s[5 * 33]); o.w = pk2(s[6 * 33], s[7 * 33]);
;         *(u32x4*)(WT + (size_t)(n0 + n) * K + k0 + 8 * c) = o; }
;     asm volatile("s_waitcnt lgkmcnt(0)" ::: "memory");
; }
	ds_write_b32 v84, v48
	v_add_u32_e32 v88, 0, v83
	v_mad_u64_u32 v[86:87], s[14:15], v88, s91, v[4:5]
	s_waitcnt vmcnt(30)
	ds_write_b32 v86, v49
	v_add_u32_e32 v88, 4, v82
	v_mad_u64_u32 v[84:85], s[14:15], v88, s91, v[4:5]
	s_waitcnt vmcnt(29)
	ds_write_b32 v84, v50
	v_add_u32_e32 v88, 4, v83
	v_mad_u64_u32 v[86:87], s[14:15], v88, s91, v[4:5]
	s_waitcnt vmcnt(28)
	ds_write_b32 v86, v51
	v_add_u32_e32 v88, 8, v82
	v_mad_u64_u32 v[84:85], s[14:15], v88, s91, v[4:5]
	s_waitcnt vmcnt(27)
	ds_write_b32 v84, v52
	v_add_u32_e32 v88, 8, v83
	v_mad_u64_u32 v[86:87], s[14:15], v88, s91, v[4:5]
	s_waitcnt vmcnt(26)
	ds_write_b32 v86, v53
	v_add_u32_e32 v88, 12, v82
	v_mad_u64_u32 v[84:85], s[14:15], v88, s91, v[4:5]
	s_waitcnt vmcnt(25)
	ds_write_b32 v84, v54
	v_add_u32_e32 v88, 12, v83
	v_mad_u64_u32 v[86:87], s[14:15], v88, s91, v[4:5]
	s_waitcnt vmcnt(24)
	ds_write_b32 v86, v55
	v_add_u32_e32 v88, 16, v82
	v_mad_u64_u32 v[84:85], s[14:15], v88, s91, v[4:5]
	s_waitcnt vmcnt(23)
	ds_write_b32 v84, v56
	v_add_u32_e32 v88, 16, v83
	v_mad_u64_u32 v[86:87], s[14:15], v88, s91, v[4:5]
	s_waitcnt vmcnt(22)
	ds_write_b32 v86, v57
	v_add_u32_e32 v88, 20, v82
	v_mad_u64_u32 v[84:85], s[14:15], v88, s91, v[4:5]
	s_waitcnt vmcnt(21)
	ds_write_b32 v84, v58
	v_add_u32_e32 v88, 20, v83
	v_mad_u64_u32 v[86:87], s[14:15], v88, s91, v[4:5]
	s_waitcnt vmcnt(20)
	ds_write_b32 v86, v59
	v_add_u32_e32 v88, 24, v82
	v_mad_u64_u32 v[84:85], s[14:15], v88, s91, v[4:5]
	s_waitcnt vmcnt(19)
	ds_write_b32 v84, v60
	v_add_u32_e32 v88, 24, v83
	v_mad_u64_u32 v[86:87], s[14:15], v88, s91, v[4:5]
	s_waitcnt vmcnt(18)
	ds_write_b32 v86, v61
	v_add_u32_e32 v88, 28, v82
	v_mad_u64_u32 v[84:85], s[14:15], v88, s91, v[4:5]
	s_waitcnt vmcnt(17)
	ds_write_b32 v84, v62
	v_add_u32_e32 v88, 28, v83
	v_mad_u64_u32 v[86:87], s[14:15], v88, s91, v[4:5]
	s_waitcnt vmcnt(16)
	ds_write_b32 v86, v63
	v_add_u32_e32 v88, 32, v82
	v_mad_u64_u32 v[84:85], s[14:15], v88, s91, v[4:5]
	s_waitcnt vmcnt(15)
	ds_write_b32 v84, v64
	v_add_u32_e32 v88, 32, v83
	v_mad_u64_u32 v[86:87], s[14:15], v88, s91, v[4:5]
	s_waitcnt vmcnt(14)
	ds_write_b32 v86, v65
	v_add_u32_e32 v88, 36, v82
	v_mad_u64_u32 v[84:85], s[14:15], v88, s91, v[4:5]
	s_waitcnt vmcnt(13)
	ds_write_b32 v84, v66
	v_add_u32_e32 v88, 36, v83
	v_mad_u64_u32 v[86:87], s[14:15], v88, s91, v[4:5]
	s_waitcnt vmcnt(12)
	ds_write_b32 v86, v67
	v_add_u32_e32 v88, 40, v82
	v_mad_u64_u32 v[84:85], s[14:15], v88, s91, v[4:5]
	s_waitcnt vmcnt(11)
	ds_write_b32 v84, v68
	v_add_u32_e32 v88, 40, v83
	v_mad_u64_u32 v[86:87], s[14:15], v88, s91, v[4:5]
	s_waitcnt vmcnt(10)
	ds_write_b32 v86, v69
	v_add_u32_e32 v88, 44, v82
	v_mad_u64_u32 v[84:85], s[14:15], v88, s91, v[4:5]
	s_waitcnt vmcnt(9)
	ds_write_b32 v84, v70
	v_add_u32_e32 v88, 44, v83
	v_mad_u64_u32 v[86:87], s[14:15], v88, s91, v[4:5]
	s_waitcnt vmcnt(8)
	ds_write_b32 v86, v71
	v_add_u32_e32 v88, 48, v82
	v_mad_u64_u32 v[84:85], s[14:15], v88, s91, v[4:5]
	s_waitcnt vmcnt(7)
	ds_write_b32 v84, v72
	v_add_u32_e32 v88, 48, v83
	v_mad_u64_u32 v[86:87], s[14:15], v88, s91, v[4:5]
	s_waitcnt vmcnt(6)
	ds_write_b32 v86, v73
	v_add_u32_e32 v88, 52, v82
	v_mad_u64_u32 v[84:85], s[14:15], v88, s91, v[4:5]
	s_waitcnt vmcnt(5)
	ds_write_b32 v84, v74
	v_add_u32_e32 v88, 52, v83
	v_mad_u64_u32 v[86:87], s[14:15], v88, s91, v[4:5]
	s_waitcnt vmcnt(4)
	ds_write_b32 v86, v75
	v_add_u32_e32 v88, 56, v82
	v_mad_u64_u32 v[84:85], s[14:15], v88, s91, v[4:5]
	s_waitcnt vmcnt(3)
	ds_write_b32 v84, v76
	v_add_u32_e32 v88, 56, v83
	v_mad_u64_u32 v[86:87], s[14:15], v88, s91, v[4:5]
	s_waitcnt vmcnt(2)
	ds_write_b32 v86, v77
	v_add_u32_e32 v88, 60, v82
	v_mad_u64_u32 v[84:85], s[14:15], v88, s91, v[4:5]
	s_waitcnt vmcnt(1)
	ds_write_b32 v84, v78
	v_add_u32_e32 v88, 60, v83
	v_mad_u64_u32 v[86:87], s[14:15], v88, s91, v[4:5]
	s_waitcnt vmcnt(0)
	ds_write_b32 v86, v79
	s_add_i32 s10, s10, 32
	s_add_i32 s2, s2, 32
	s_add_i32 s11, s11, -32
	s_cmp_lg_u32 s11, 0
	s_cbranch_scc1 .Lcw_gather2
	v_mov_b32_e32 v17, v1
	v_readlane_b32 s10, v250, 41
	v_lshlrev_b64 v[16:17], 20, v[16:17]
	v_readlane_b32 s11, v250, 42
	s_waitcnt lgkmcnt(0)
	v_lshlrev_b32_e32 v0, 1, v27
	ds_read2_b32 v[30:31], v23 offset0:33 offset1:41
	ds_read2_b32 v[32:33], v23 offset1:8
	v_lshl_add_u64 v[16:17], s[10:11], 0, v[16:17]
	ds_read2_b32 v[34:35], v23 offset0:66 offset1:74
	ds_read2_b32 v[36:37], v23 offset0:99 offset1:107
	ds_read2_b32 v[38:39], v23 offset0:132 offset1:140
	ds_read2_b32 v[40:41], v23 offset0:165 offset1:173
	ds_read2_b32 v[42:43], v23 offset0:198 offset1:206
	ds_read2_b32 v[44:45], v23 offset0:231 offset1:239
	v_lshl_add_u64 v[16:17], v[16:17], 0, v[0:1]
	v_lshlrev_b32_e32 v0, 1, v6
	v_lshl_add_u64 v[28:29], v[16:17], 0, v[0:1]
	v_or_b32_e32 v0, v21, v22
	v_lshlrev_b32_e32 v0, 10, v0
	v_lshl_add_u64 v[46:47], v[28:29], 0, v[0:1]
	v_or_b32_e32 v0, v21, v24
	s_waitcnt lgkmcnt(6)
	v_cvt_pk_bf16_f32 v16, v32, v30
	s_waitcnt lgkmcnt(4)
	v_cvt_pk_bf16_f32 v17, v34, v36
	s_waitcnt lgkmcnt(2)
	v_cvt_pk_bf16_f32 v18, v38, v40
	s_waitcnt lgkmcnt(0)
	v_cvt_pk_bf16_f32 v19, v42, v44
	v_lshlrev_b32_e32 v0, 10, v0
	global_store_dwordx4 v[46:47], v[16:19], off
	v_readlane_b32 s16, v254, 46
	s_nop 0
	v_cvt_pk_bf16_f32 v16, v33, v31
	v_cvt_pk_bf16_f32 v17, v35, v37
	v_cvt_pk_bf16_f32 v18, v39, v41
	v_cvt_pk_bf16_f32 v19, v43, v45
	v_lshl_add_u64 v[30:31], v[28:29], 0, v[0:1]
	global_store_dwordx4 v[30:31], v[16:19], off
	ds_read2_b32 v[30:31], v23 offset0:49 offset1:57
	ds_read2_b32 v[32:33], v23 offset0:16 offset1:24
	ds_read2_b32 v[34:35], v23 offset0:82 offset1:90
	ds_read2_b32 v[36:37], v23 offset0:115 offset1:123
	ds_read2_b32 v[38:39], v23 offset0:148 offset1:156
	ds_read2_b32 v[40:41], v23 offset0:181 offset1:189
	ds_read2_b32 v[42:43], v23 offset0:214 offset1:222
	ds_read2_b32 v[44:45], v23 offset0:247 offset1:255
	v_or_b32_e32 v0, v21, v25
	v_lshlrev_b32_e32 v0, 10, v0
	v_lshl_add_u64 v[46:47], v[28:29], 0, v[0:1]
	v_or_b32_e32 v0, v21, v26
	s_waitcnt lgkmcnt(6)
	v_cvt_pk_bf16_f32 v16, v32, v30
	s_waitcnt lgkmcnt(4)
	v_cvt_pk_bf16_f32 v17, v34, v36
	s_waitcnt lgkmcnt(2)
	v_cvt_pk_bf16_f32 v18, v38, v40
	s_waitcnt lgkmcnt(0)
	v_cvt_pk_bf16_f32 v19, v42, v44
	v_lshlrev_b32_e32 v0, 10, v0
	global_store_dwordx4 v[46:47], v[16:19], off
	v_lshl_add_u64 v[20:21], v[28:29], 0, v[0:1]
	s_nop 0
	v_cvt_pk_bf16_f32 v16, v33, v31
	v_cvt_pk_bf16_f32 v17, v35, v37
	v_cvt_pk_bf16_f32 v18, v39, v41
	v_cvt_pk_bf16_f32 v19, v43, v45
	global_store_dwordx4 v[20:21], v[16:19], off
	s_waitcnt lgkmcnt(0)

; #define LAS __attribute__((address_space(3)))
; __device__ __forceinline__ void transpose_item(const float* W, int K, int N, bf16_t* WT, LAS float* scr, int item, int lane) {
;     const int nblk = N / 32, kb = item / nblk, nb = item % nblk, k0 = 64 * kb, n0 = 32 * nb;
; #pragma unroll 8
;     for (int i = 0; i < 32; ++i) { const int kk = 2 * i + (lane >> 5); scr[kk * 33 + (lane & 31)] = W[(size_t)(k0 + kk) * N + n0 + (lane & 31)]; }
;     asm volatile("s_waitcnt lgkmcnt(0)" ::: "memory");
.Lcw_gather3:
	s_lshl_b32 s11, s8, 1
	s_lshl_b32 s10, s2, 1
	v_or_b32_e32 v80, s11, v0
	v_or_b32_e32 v81, s10, v5
	v_or_b32_e32 v82, s11, v2
	v_or_b32_e32 v83, s10, v3
	v_add_u32_e32 v88, 0, v80
	v_mad_i64_i32 v[84:85], s[12:13], v88, s81, v[20:21]
	global_load_dword v48, v[84:85], off
	v_add_u32_e32 v88, 0, v81
	v_mad_i64_i32 v[86:87], s[12:13], v88, s81, v[20:21]
	global_load_dword v49, v[86:87], off
	v_add_u32_e32 v88, 4, v80
	v_mad_i64_i32 v[84:85], s[12:13], v88, s81, v[20:21]
	global_load_dword v50, v[84:85], off
	v_add_u32_e32 v88, 4, v81
	v_mad_i64_i32 v[86:87], s[12:13], v88, s81, v[20:21]
	global_load_dword v51, v[86:87], off
	v_add_u32_e32 v88, 8, v80
	v_mad_i64_i32 v[84:85], s[12:13], v88, s81, v[20:21]
	global_load_dword v52, v[84:85], off
	v_add_u32_e32 v88, 8, v81
	v_mad_i64_i32 v[86:87], s[12:13], v88, s81, v[20:21]
	global_load_dword v53, v[86:87], off
	v_add_u32_e32 v88, 12, v80
	v_mad_i64_i32 v[84:85], s[12:13], v88, s81, v[20:21]
	global_load_dword v54, v[84:85], off
	v_add_u32_e32 v88, 12, v81
	v_mad_i64_i32 v[86:87], s[12:13], v88, s81, v[20:21]
	global_load_dword v55, v[86:87], off
	v_add_u32_e32 v88, 16, v80
	v_mad_i64_i32 v[84:85], s[12:13], v88, s81, v[20:21]
	global_load_dword v56, v[84:85], off
	v_add_u32_e32 v88, 16, v81
	v_mad_i64_i32 v[86:87], s[12:13], v88, s81, v[20:21]
	global_load_dword v57, v[86:87], off
	v_add_u32_e32 v88, 20, v80
	v_mad_i64_i32 v[84:85], s[12:13], v88, s81, v[20:21]
	global_load_dword v58, v[84:85], off
	v_add_u32_e32 v88, 20, v81
	v_mad_i64_i32 v[86:87], s[12:13], v88, s81, v[20:21]
	global_load_dword v59, v[86:87], off
	v_add_u32_e32 v88, 24, v80
	v_mad_i64_i32 v[84:85], s[12:13], v88, s81, v[20:21]
	global_load_dword v60, v[84:85], off
	v_add_u32_e32 v88, 24, v81
	v_mad_i64_i32 v[86:87], s[12:13], v88, s81, v[20:21]
	global_load_dword v61, v[86:87], off
	v_add_u32_e32 v88, 28, v80
	v_mad_i64_i32 v[84:85], s[12:13], v88, s81, v[20:21]
	global_load_dword v62, v[84:85], off
	v_add_u32_e32 v88, 28, v81
	v_mad_i64_i32 v[86:87], s[12:13], v88, s81, v[20:21]
	global_load_dword v63, v[86:87], off
	v_add_u32_e32 v88, 32, v80
	v_mad_i64_i32 v[84:85], s[12:13], v88, s81, v[20:21]
	global_load_dword v64, v[84:85], off
	v_add_u32_e32 v88, 32, v81
	v_mad_i64_i32 v[86:87], s[12:13], v88, s81, v[20:21]
	global_load_dword v65, v[86:87], off
	v_add_u32_e32 v88, 36, v80
	v_mad_i64_i32 v[84:85], s[12:13], v88, s81, v[20:21]
	global_load_dword v66, v[84:85], off
	v_add_u32_e32 v88, 36, v81
	v_mad_i64_i32 v[86:87], s[12:13], v88, s81, v[20:21]
	global_load_dword v67, v[86:87], off
	v_add_u32_e32 v88, 40, v80
	v_mad_i64_i32 v[84:85], s[12:13], v88, s81, v[20:21]
	global_load_dword v68, v[84:85], off
	v_add_u32_e32 v88, 40, v81
	v_mad_i64_i32 v[86:87], s[12:13], v88, s81, v[20:21]
	global_load_dword v69, v[86:87], off
	v_add_u32_e32 v88, 44, v80
	v_mad_i64_i32 v[84:85], s[12:13], v88, s81, v[20:21]
	global_load_dword v70, v[84:85], off
	v_add_u32_e32 v88, 44, v81
	v_mad_i64_i32 v[86:87], s[12:13], v88, s81, v[20:21]
	global_load_dword v71, v[86:87], off
	v_add_u32_e32 v88, 48, v80
	v_mad_i64_i32 v[84:85], s[12:13], v88, s81, v[20:21]
	global_load_dword v72, v[84:85], off
	v_add_u32_e32 v88, 48, v81
	v_mad_i64_i32 v[86:87], s[12:13], v88, s81, v[20:21]
	global_load_dword v73, v[86:87], off
	v_add_u32_e32 v88, 52, v80
	v_mad_i64_i32 v[84:85], s[12:13], v88, s81, v[20:21]
	global_load_dword v74, v[84:85], off
	v_add_u32_e32 v88, 52, v81
	v_mad_i64_i32 v[86:87], s[12:13], v88, s81, v[20:21]
	global_load_dword v75, v[86:87], off
	v_add_u32_e32 v88, 56, v80
	v_mad_i64_i32 v[84:85], s[12:13], v88, s81, v[20:21]
	global_load_dword v76, v[84:85], off
	v_add_u32_e32 v88, 56, v81
	v_mad_i64_i32 v[86:87], s[12:13], v88, s81, v[20:21]
	global_load_dword v77, v[86:87], off
	v_add_u32_e32 v88, 60, v80
	v_mad_i64_i32 v[84:85], s[12:13], v88, s81, v[20:21]
	global_load_dword v78, v[84:85], off
	v_add_u32_e32 v88, 60, v81
	v_mad_i64_i32 v[86:87], s[12:13], v88, s81, v[20:21]
	global_load_dword v79, v[86:87], off
	v_add_u32_e32 v88, 0, v82
	v_mad_u64_u32 v[84:85], s[12:13], v88, s91, v[4:5]
	s_waitcnt vmcnt(31)
	ds_write_b32 v84, v48
	v_add_u32_e32 v88, 0, v83
	v_mad_u64_u32 v[86:87], s[12:13], v88, s91, v[4:5]
	s_waitcnt vmcnt(30)
	ds_write_b32 v86, v49
	v_add_u32_e32 v88, 4, v82
	v_mad_u64_u32 v[84:85], s[12:13], v88, s91, v[4:5]
	s_waitcnt vmcnt(29)
	ds_write_b32 v84, v50
	v_add_u32_e32 v88, 4, v83
	v_mad_u64_u32 v[86:87], s[12:13], v88, s91, v[4:5]
	s_waitcnt vmcnt(28)
	ds_write_b32 v86, v51
	v_add_u32_e32 v88, 8, v82
	v_mad_u64_u32 v[84:85], s[12:13], v88, s91, v[4:5]
	s_waitcnt vmcnt(27)
	ds_write_b32 v84, v52
	v_add_u32_e32 v88, 8, v83
	v_mad_u64_u32 v[86:87], s[12:13], v88, s91, v[4:5]
	s_waitcnt vmcnt(26)
	ds_write_b32 v86, v53
	v_add_u32_e32 v88, 12, v82
	v_mad_u64_u32 v[84:85], s[12:13], v88, s91, v[4:5]
	s_waitcnt vmcnt(25)
	ds_write_b32 v84, v54
	v_add_u32_e32 v88, 12, v83
	v_mad_u64_u32 v[86:87], s[12:13], v88, s91, v[4:5]
	s_waitcnt vmcnt(24)
	ds_write_b32 v86, v55
	v_add_u32_e32 v88, 16, v82
	v_mad_u64_u32 v[84:85], s[12:13], v88, s91, v[4:5]
	s_waitcnt vmcnt(23)
	ds_write_b32 v84, v56
	v_add_u32_e32 v88, 16, v83
	v_mad_u64_u32 v[86:87], s[12:13], v88, s91, v[4:5]
	s_waitcnt vmcnt(22)
	ds_write_b32 v86, v57
	v_add_u32_e32 v88, 20, v82
	v_mad_u64_u32 v[84:85], s[12:13], v88, s91, v[4:5]
	s_waitcnt vmcnt(21)
; #define LAS __attribute__((address_space(3)))
; __device__ __forceinline__ unsigned pk2(float lo, float hi) { f32x2 v = {lo, hi}; hbf16x2 b = __builtin_convertvector(v, hbf16x2); return __builtin_bit_cast(unsigned, b); }
; __device__ __forceinline__ void transpose_item(const float* W, int K, int N, bf16_t* WT, LAS float* scr, int item, int lane) {
;     ...
;     for (int i = 0; i < 32; ++i) { const int kk = 2 * i + (lane >> 5); scr[kk * 33 + (lane & 31)] = W[(size_t)(k0 + kk) * N + n0 + (lane & 31)]; }
;     asm volatile("s_waitcnt lgkmcnt(0)" ::: "memory");
;     const int c = lane & 7;
; #pragma unroll
;     for (int j = 0; j < 4; ++j) { const int n = (lane >> 3) + 8 * j; const LAS float* s = scr + (8 * c) * 33 + n;
;         u32x4 o; o.x = pk2(s[0 * 33], s[1 * 33]); o.y = pk2(s[2 * 33], s[3 * 33]); o.z = pk2(s[4 * 33], s[5 * 33]); o.w = pk2(s[6 * 33], s[7 * 33]);
;         *(u32x4*)(WT + (size_t)(n0 + n) * K + k0 + 8 * c) = o; }
;     asm volatile("s_waitcnt lgkmcnt(0)" ::: "memory");
; }
; __device__ __forceinline__ void convert_weights(const Params& p, int l, unsigned char* lds) {
;     ...
;         if (r < I_IN) { transpose_item(p.in[I_WIN] + (size_t)l * 1024 * DIN, 1024, DIN, ((r % (DIN / 32)) * 32 < 1792) ? winrw : win2, scr, r, lane); continue; } r -= I_IN;
	ds_write_b32 v84, v58
	v_add_u32_e32 v88, 20, v83
	v_mad_u64_u32 v[86:87], s[12:13], v88, s91, v[4:5]
	s_waitcnt vmcnt(20)
	ds_write_b32 v86, v59
	v_add_u32_e32 v88, 24, v82
	v_mad_u64_u32 v[84:85], s[12:13], v88, s91, v[4:5]
	s_waitcnt vmcnt(19)
	ds_write_b32 v84, v60
	v_add_u32_e32 v88, 24, v83
	v_mad_u64_u32 v[86:87], s[12:13], v88, s91, v[4:5]
	s_waitcnt vmcnt(18)
	ds_write_b32 v86, v61
	v_add_u32_e32 v88, 28, v82
	v_mad_u64_u32 v[84:85], s[12:13], v88, s91, v[4:5]
	s_waitcnt vmcnt(17)
	ds_write_b32 v84, v62
	v_add_u32_e32 v88, 28, v83
	v_mad_u64_u32 v[86:87], s[12:13], v88, s91, v[4:5]
	s_waitcnt vmcnt(16)
	ds_write_b32 v86, v63
	v_add_u32_e32 v88, 32, v82
	v_mad_u64_u32 v[84:85], s[12:13], v88, s91, v[4:5]
	s_waitcnt vmcnt(15)
	ds_write_b32 v84, v64
	v_add_u32_e32 v88, 32, v83
	v_mad_u64_u32 v[86:87], s[12:13], v88, s91, v[4:5]
	s_waitcnt vmcnt(14)
	ds_write_b32 v86, v65
	v_add_u32_e32 v88, 36, v82
	v_mad_u64_u32 v[84:85], s[12:13], v88, s91, v[4:5]
	s_waitcnt vmcnt(13)
	ds_write_b32 v84, v66
	v_add_u32_e32 v88, 36, v83
	v_mad_u64_u32 v[86:87], s[12:13], v88, s91, v[4:5]
	s_waitcnt vmcnt(12)
	ds_write_b32 v86, v67
	v_add_u32_e32 v88, 40, v82
	v_mad_u64_u32 v[84:85], s[12:13], v88, s91, v[4:5]
	s_waitcnt vmcnt(11)
	ds_write_b32 v84, v68
	v_add_u32_e32 v88, 40, v83
	v_mad_u64_u32 v[86:87], s[12:13], v88, s91, v[4:5]
	s_waitcnt vmcnt(10)
	ds_write_b32 v86, v69
	v_add_u32_e32 v88, 44, v82
	v_mad_u64_u32 v[84:85], s[12:13], v88, s91, v[4:5]
	s_waitcnt vmcnt(9)
	ds_write_b32 v84, v70
	v_add_u32_e32 v88, 44, v83
	v_mad_u64_u32 v[86:87], s[12:13], v88, s91, v[4:5]
	s_waitcnt vmcnt(8)
	ds_write_b32 v86, v71
	v_add_u32_e32 v88, 48, v82
	v_mad_u64_u32 v[84:85], s[12:13], v88, s91, v[4:5]
	s_waitcnt vmcnt(7)
	ds_write_b32 v84, v72
	v_add_u32_e32 v88, 48, v83
	v_mad_u64_u32 v[86:87], s[12:13], v88, s91, v[4:5]
	s_waitcnt vmcnt(6)
	ds_write_b32 v86, v73
	v_add_u32_e32 v88, 52, v82
	v_mad_u64_u32 v[84:85], s[12:13], v88, s91, v[4:5]
	s_waitcnt vmcnt(5)
	ds_write_b32 v84, v74
	v_add_u32_e32 v88, 52, v83
	v_mad_u64_u32 v[86:87], s[12:13], v88, s91, v[4:5]
	s_waitcnt vmcnt(4)
	ds_write_b32 v86, v75
	v_add_u32_e32 v88, 56, v82
	v_mad_u64_u32 v[84:85], s[12:13], v88, s91, v[4:5]
	s_waitcnt vmcnt(3)
	ds_write_b32 v84, v76
	v_add_u32_e32 v88, 56, v83
	v_mad_u64_u32 v[86:87], s[12:13], v88, s91, v[4:5]
	s_waitcnt vmcnt(2)
	ds_write_b32 v86, v77
	v_add_u32_e32 v88, 60, v82
	v_mad_u64_u32 v[84:85], s[12:13], v88, s91, v[4:5]
	s_waitcnt vmcnt(1)
	ds_write_b32 v84, v78
	v_add_u32_e32 v88, 60, v83
	v_mad_u64_u32 v[86:87], s[12:13], v88, s91, v[4:5]
	s_waitcnt vmcnt(0)
	ds_write_b32 v86, v79
	s_add_i32 s8, s8, 32
	s_add_i32 s2, s2, 32
	s_add_i32 s9, s9, -32
	s_cmp_lg_u32 s9, 0
	s_cbranch_scc1 .Lcw_gather3
	s_waitcnt lgkmcnt(0)
	v_cmp_gt_i32_e32 vcc, 56, v15
	ds_read2_b32 v[30:31], v23 offset0:33 offset1:41
	ds_read2_b32 v[32:33], v23 offset1:8
	ds_read2_b32 v[34:35], v23 offset0:66 offset1:74
	ds_read2_b32 v[36:37], v23 offset0:99 offset1:107
	ds_read2_b32 v[38:39], v23 offset0:132 offset1:140
	ds_read2_b32 v[40:41], v23 offset0:165 offset1:173
	ds_read2_b32 v[42:43], v23 offset0:198 offset1:206
	ds_read2_b32 v[44:45], v23 offset0:231 offset1:239
	v_cndmask_b32_e32 v0, v235, v236, vcc
	v_lshl_add_u64 v[20:21], s[72:73], 0, v[0:1]
	v_ashrrev_i32_e32 v19, 31, v18
	v_or_b32_e32 v46, v16, v22
	v_lshl_add_u64 v[18:19], v[18:19], 1, v[20:21]
	v_lshlrev_b32_e32 v0, 1, v6
	v_ashrrev_i32_e32 v47, 31, v46
	v_lshl_add_u64 v[28:29], v[18:19], 0, v[0:1]
	v_lshlrev_b64 v[46:47], 11, v[46:47]
	s_waitcnt lgkmcnt(6)
	v_cvt_pk_bf16_f32 v18, v32, v30
	s_waitcnt lgkmcnt(4)
	v_cvt_pk_bf16_f32 v19, v34, v36
	s_waitcnt lgkmcnt(2)
	v_cvt_pk_bf16_f32 v20, v38, v40
	s_waitcnt lgkmcnt(0)
	v_cvt_pk_bf16_f32 v21, v42, v44
	v_lshl_add_u64 v[46:47], v[28:29], 0, v[46:47]
	v_or_b32_e32 v30, v16, v24
	global_store_dwordx4 v[46:47], v[18:21], off
	v_or_b32_e32 v46, v16, v25
	v_ashrrev_i32_e32 v47, 31, v46
	v_cvt_pk_bf16_f32 v18, v33, v31
	v_ashrrev_i32_e32 v31, 31, v30
	v_lshlrev_b64 v[30:31], 11, v[30:31]
	v_cvt_pk_bf16_f32 v19, v35, v37
	v_cvt_pk_bf16_f32 v20, v39, v41
	v_cvt_pk_bf16_f32 v21, v43, v45
	v_lshl_add_u64 v[30:31], v[28:29], 0, v[30:31]
	global_store_dwordx4 v[30:31], v[18:21], off
	ds_read2_b32 v[30:31], v23 offset0:49 offset1:57
	ds_read2_b32 v[32:33], v23 offset0:16 offset1:24
	ds_read2_b32 v[34:35], v23 offset0:82 offset1:90
	ds_read2_b32 v[36:37], v23 offset0:115 offset1:123
	ds_read2_b32 v[38:39], v23 offset0:148 offset1:156
	ds_read2_b32 v[40:41], v23 offset0:181 offset1:189
	ds_read2_b32 v[42:43], v23 offset0:214 offset1:222
	ds_read2_b32 v[44:45], v23 offset0:247 offset1:255
	v_or_b32_e32 v16, v16, v26
	v_lshlrev_b64 v[46:47], 11, v[46:47]
	v_ashrrev_i32_e32 v17, 31, v16
	s_waitcnt lgkmcnt(6)
	v_cvt_pk_bf16_f32 v18, v32, v30
	s_waitcnt lgkmcnt(4)
	v_cvt_pk_bf16_f32 v19, v34, v36
	s_waitcnt lgkmcnt(2)
	v_cvt_pk_bf16_f32 v20, v38, v40
	s_waitcnt lgkmcnt(0)
	v_cvt_pk_bf16_f32 v21, v42, v44
	v_lshl_add_u64 v[46:47], v[28:29], 0, v[46:47]
	v_lshlrev_b64 v[16:17], 11, v[16:17]
	global_store_dwordx4 v[46:47], v[18:21], off
	v_lshl_add_u64 v[16:17], v[28:29], 0, v[16:17]
	s_nop 0
	v_cvt_pk_bf16_f32 v18, v33, v31
	v_cvt_pk_bf16_f32 v19, v35, v37
	v_cvt_pk_bf16_f32 v20, v39, v41
	v_cvt_pk_bf16_f32 v21, v43, v45
	global_store_dwordx4 v[16:17], v[18:21], off
	s_waitcnt lgkmcnt(0)
	s_branch .LBB0_1261
